# P4 compress item, second stage: 64 weight loads in flight per trip (4x fewer load round trips) with counted waits
# baseline (speedup 1.0000x reference)
.LBB0_640:
	v_lshl_add_u64 v[10:11], v[4:5], 0, s[10:11]
	global_load_dword v44, v[10:11], off
	global_load_dword v45, v[10:11], off offset:256
	global_load_dword v46, v[10:11], off offset:512
	global_load_dword v47, v[10:11], off offset:768
	global_load_dword v48, v[10:11], off offset:1024
	global_load_dword v49, v[10:11], off offset:1280
	global_load_dword v50, v[10:11], off offset:1536
	global_load_dword v51, v[10:11], off offset:1792
	global_load_dword v52, v[10:11], off offset:2048
	global_load_dword v53, v[10:11], off offset:2304
	global_load_dword v54, v[10:11], off offset:2560
	global_load_dword v55, v[10:11], off offset:2816
	global_load_dword v56, v[10:11], off offset:3072
	global_load_dword v57, v[10:11], off offset:3328
	global_load_dword v58, v[10:11], off offset:3584
	global_load_dword v59, v[10:11], off offset:3840
	s_add_u32 s10, s10, 0x1000
	s_addc_u32 s11, s11, 0
	v_lshl_add_u64 v[10:11], v[4:5], 0, s[10:11]
	global_load_dword v60, v[10:11], off
	global_load_dword v61, v[10:11], off offset:256
	global_load_dword v62, v[10:11], off offset:512
	global_load_dword v63, v[10:11], off offset:768
	global_load_dword v64, v[10:11], off offset:1024
	global_load_dword v65, v[10:11], off offset:1280
	global_load_dword v66, v[10:11], off offset:1536
	global_load_dword v67, v[10:11], off offset:1792
	global_load_dword v68, v[10:11], off offset:2048
	global_load_dword v69, v[10:11], off offset:2304
	global_load_dword v70, v[10:11], off offset:2560
	global_load_dword v71, v[10:11], off offset:2816
	global_load_dword v72, v[10:11], off offset:3072
	global_load_dword v73, v[10:11], off offset:3328
	global_load_dword v74, v[10:11], off offset:3584
	global_load_dword v75, v[10:11], off offset:3840
	s_add_u32 s10, s10, 0x1000
	s_addc_u32 s11, s11, 0
	v_lshl_add_u64 v[10:11], v[4:5], 0, s[10:11]
	global_load_dword v76, v[10:11], off
	global_load_dword v77, v[10:11], off offset:256
	global_load_dword v78, v[10:11], off offset:512
	global_load_dword v79, v[10:11], off offset:768
	global_load_dword v80, v[10:11], off offset:1024
	global_load_dword v81, v[10:11], off offset:1280
	global_load_dword v82, v[10:11], off offset:1536
	global_load_dword v83, v[10:11], off offset:1792
	global_load_dword v84, v[10:11], off offset:2048
	global_load_dword v85, v[10:11], off offset:2304
	global_load_dword v86, v[10:11], off offset:2560
	global_load_dword v87, v[10:11], off offset:2816
	global_load_dword v88, v[10:11], off offset:3072
	global_load_dword v89, v[10:11], off offset:3328
	global_load_dword v90, v[10:11], off offset:3584
	global_load_dword v91, v[10:11], off offset:3840
	s_add_u32 s10, s10, 0x1000
	s_addc_u32 s11, s11, 0
	v_lshl_add_u64 v[10:11], v[4:5], 0, s[10:11]
	global_load_dword v92, v[10:11], off
	global_load_dword v93, v[10:11], off offset:256
	global_load_dword v94, v[10:11], off offset:512
	global_load_dword v95, v[10:11], off offset:768
	global_load_dword v96, v[10:11], off offset:1024
	global_load_dword v97, v[10:11], off offset:1280
	global_load_dword v98, v[10:11], off offset:1536
	global_load_dword v99, v[10:11], off offset:1792
	global_load_dword v100, v[10:11], off offset:2048
	global_load_dword v101, v[10:11], off offset:2304
	global_load_dword v102, v[10:11], off offset:2560
	global_load_dword v103, v[10:11], off offset:2816
	global_load_dword v104, v[10:11], off offset:3072
	global_load_dword v105, v[10:11], off offset:3328
	global_load_dword v106, v[10:11], off offset:3584
	global_load_dword v107, v[10:11], off offset:3840
	s_add_u32 s10, s10, 0x1000
	s_addc_u32 s11, s11, 0
	ds_read_b128 v[10:13], v9
	ds_read_b128 v[18:21], v9 offset:16
	ds_read_b128 v[26:29], v9 offset:32
	ds_read_b128 v[30:33], v9 offset:48
	v_add_u32_e32 v9, 64, v9
	s_waitcnt vmcnt(48) lgkmcnt(0)
	v_fmac_f32_e32 v0, v10, v44
	v_fmac_f32_e32 v0, v11, v45
	v_fmac_f32_e32 v0, v12, v46
	v_fmac_f32_e32 v0, v13, v47
	v_fmac_f32_e32 v0, v18, v48
	v_fmac_f32_e32 v0, v19, v49
	v_fmac_f32_e32 v0, v20, v50
	v_fmac_f32_e32 v0, v21, v51
	v_fmac_f32_e32 v0, v26, v52
	v_fmac_f32_e32 v0, v27, v53
	v_fmac_f32_e32 v0, v28, v54
	v_fmac_f32_e32 v0, v29, v55
	v_fmac_f32_e32 v0, v30, v56
	v_fmac_f32_e32 v0, v31, v57
	v_fmac_f32_e32 v0, v32, v58
	v_fmac_f32_e32 v0, v33, v59
	ds_read_b128 v[10:13], v9
	ds_read_b128 v[18:21], v9 offset:16
	ds_read_b128 v[26:29], v9 offset:32
	ds_read_b128 v[30:33], v9 offset:48
	v_add_u32_e32 v9, 64, v9
	s_waitcnt vmcnt(32) lgkmcnt(0)
	v_fmac_f32_e32 v0, v10, v60
	v_fmac_f32_e32 v0, v11, v61
	v_fmac_f32_e32 v0, v12, v62
	v_fmac_f32_e32 v0, v13, v63
	v_fmac_f32_e32 v0, v18, v64
	v_fmac_f32_e32 v0, v19, v65
	v_fmac_f32_e32 v0, v20, v66
	v_fmac_f32_e32 v0, v21, v67
	v_fmac_f32_e32 v0, v26, v68
	v_fmac_f32_e32 v0, v27, v69
	v_fmac_f32_e32 v0, v28, v70
	v_fmac_f32_e32 v0, v29, v71
	v_fmac_f32_e32 v0, v30, v72
	v_fmac_f32_e32 v0, v31, v73
	v_fmac_f32_e32 v0, v32, v74
	v_fmac_f32_e32 v0, v33, v75
	ds_read_b128 v[10:13], v9
	ds_read_b128 v[18:21], v9 offset:16
	ds_read_b128 v[26:29], v9 offset:32
	ds_read_b128 v[30:33], v9 offset:48
	v_add_u32_e32 v9, 64, v9
	s_waitcnt vmcnt(16) lgkmcnt(0)
	v_fmac_f32_e32 v0, v10, v76
	v_fmac_f32_e32 v0, v11, v77
	v_fmac_f32_e32 v0, v12, v78
	v_fmac_f32_e32 v0, v13, v79
	v_fmac_f32_e32 v0, v18, v80
	v_fmac_f32_e32 v0, v19, v81
	v_fmac_f32_e32 v0, v20, v82
	v_fmac_f32_e32 v0, v21, v83
	v_fmac_f32_e32 v0, v26, v84
	v_fmac_f32_e32 v0, v27, v85
	v_fmac_f32_e32 v0, v28, v86
	v_fmac_f32_e32 v0, v29, v87
	v_fmac_f32_e32 v0, v30, v88
	v_fmac_f32_e32 v0, v31, v89
	v_fmac_f32_e32 v0, v32, v90
	v_fmac_f32_e32 v0, v33, v91
	ds_read_b128 v[10:13], v9
	ds_read_b128 v[18:21], v9 offset:16
	ds_read_b128 v[26:29], v9 offset:32
	ds_read_b128 v[30:33], v9 offset:48
	v_add_u32_e32 v9, 64, v9
	s_waitcnt vmcnt(0) lgkmcnt(0)
	v_fmac_f32_e32 v0, v10, v92
	v_fmac_f32_e32 v0, v11, v93
	v_fmac_f32_e32 v0, v12, v94
	v_fmac_f32_e32 v0, v13, v95
	v_fmac_f32_e32 v0, v18, v96
	v_fmac_f32_e32 v0, v19, v97
	v_fmac_f32_e32 v0, v20, v98
	v_fmac_f32_e32 v0, v21, v99
	v_fmac_f32_e32 v0, v26, v100
	v_fmac_f32_e32 v0, v27, v101
	v_fmac_f32_e32 v0, v28, v102
	v_fmac_f32_e32 v0, v29, v103
	v_fmac_f32_e32 v0, v30, v104
	v_fmac_f32_e32 v0, v31, v105
	v_fmac_f32_e32 v0, v32, v106
	v_fmac_f32_e32 v0, v33, v107
	s_cmpk_eq_u32 s10, 0x8000
	s_cbranch_scc0 .LBB0_640
	v_add_u32_e32 v11, s5, v8
	v_bfe_u32 v9, v0, 16, 1
	v_cmp_gt_i32_e32 vcc, s85, v11
	v_add3_u32 v0, v0, v9, s97
	v_ashrrev_i32_e32 v10, 5, v11
	v_cndmask_b32_sdwa v9, v1, v0, vcc dst_sel:DWORD dst_unused:UNUSED_PAD src0_sel:DWORD src1_sel:WORD_1
	v_and_b32_e32 v11, 31, v11
	s_mov_b64 s[10:11], -1
	s_and_b64 vcc, exec, s[2:3]
	s_cbranch_vccz .LBB0_643
	v_lshrrev_b32_e32 v12, 4, v24
	v_lshlrev_b32_e32 v0, 2, v10
	v_and_b32_e32 v12, 2, v12
	v_lshrrev_b32_e32 v13, 4, v11
	v_or3_b32 v0, v0, v12, v13
	v_lshlrev_b32_e32 v12, 3, v8
	v_lshlrev_b32_e32 v0, 6, v0
	v_and_b32_e32 v12, 32, v12
	v_or3_b32 v0, v0, v12, v6
	v_lshlrev_b32_e32 v12, 3, v0
	v_ashrrev_i32_e32 v13, 31, v12
	v_lshrrev_b32_e32 v0, 5, v24
	v_lshl_add_u64 v[12:13], v[12:13], 1, s[6:7]
	v_and_b32_e32 v0, 6, v0
	v_lshl_add_u64 v[12:13], v[12:13], 0, v[0:1]
	v_and_b32_e32 v0, 8, v8
	v_lshl_add_u64 v[12:13], v[12:13], 0, v[0:1]
	global_store_short v[12:13], v9, off
	s_mov_b64 s[10:11], 0
